# attention shift test: one v_permlane32_swap of the two row-max accumulators (per-half maxima in the two half-waves of one register) instead of two copies + two swaps + max/min; rescale block rebuilds
# speedup vs baseline: 1.0119x; 1.0042x over previous
.LBB0_885:
	s_nop 10
	v_max_f32_e32 v203, v80, v81
	v_max_f32_e32 v205, v64, v65
	v_max3_f32 v203, v203, v82, v83
	v_max3_f32 v205, v205, v66, v67
	v_max3_f32 v203, v203, v84, v85
	v_max3_f32 v205, v205, v68, v69
	v_max3_f32 v203, v203, v86, v87
	v_max3_f32 v205, v205, v70, v71
	v_max3_f32 v203, v203, v88, v89
	v_max3_f32 v205, v205, v72, v73
	v_max3_f32 v203, v203, v90, v91
	v_max3_f32 v205, v205, v74, v75
	v_max3_f32 v203, v203, v92, v93
	v_max3_f32 v205, v205, v76, v77
	v_max3_f32 v203, v203, v94, v95
	v_max3_f32 v205, v205, v78, v79
	s_nop 1
	v_permlane32_swap_b32_e32 v203, v205
	v_max_f32_e32 v204, v203, v205
	v_cmp_lt_f32_e32 vcc, s83, v204
	s_cmp_lg_u64 s[64:65], 0
	s_cbranch_scc1 .Lhwat0_firstchk
	s_cbranch_vccz .LBB0_887
	s_branch .Lhwat0_rare
.Lhwat0_firstchk:
	v_cmp_gt_f32_e64 s[28:29], s84, v204
	s_or_b64 s[28:29], vcc, s[28:29]
	s_and_b64 vcc, exec, s[28:29]
	s_cbranch_vccz .LBB0_887
.Lhwat0_rare:
	v_mov_b32_e32 v203, v204
	s_nop 1
	v_permlane32_swap_b32_e32 v204, v203
	v_max_f32_e32 v205, v204, v204
	v_max_f32_e32 v205, 0, v205
	v_cndmask_b32_e64 v204, v205, v204, s[64:65]
	v_exp_f32_e64 v206, -v204
	v_add_f32_e32 v199, v199, v204
	v_pk_add_f32 v[80:81], v[80:81], v[204:205] op_sel_hi:[1,0] neg_lo:[0,1] neg_hi:[0,1]
	v_pk_add_f32 v[82:83], v[82:83], v[204:205] op_sel_hi:[1,0] neg_lo:[0,1] neg_hi:[0,1]
	v_pk_add_f32 v[84:85], v[84:85], v[204:205] op_sel_hi:[1,0] neg_lo:[0,1] neg_hi:[0,1]
	v_pk_add_f32 v[86:87], v[86:87], v[204:205] op_sel_hi:[1,0] neg_lo:[0,1] neg_hi:[0,1]
	v_pk_add_f32 v[88:89], v[88:89], v[204:205] op_sel_hi:[1,0] neg_lo:[0,1] neg_hi:[0,1]
	v_pk_add_f32 v[90:91], v[90:91], v[204:205] op_sel_hi:[1,0] neg_lo:[0,1] neg_hi:[0,1]
	v_pk_add_f32 v[92:93], v[92:93], v[204:205] op_sel_hi:[1,0] neg_lo:[0,1] neg_hi:[0,1]
	v_pk_add_f32 v[94:95], v[94:95], v[204:205] op_sel_hi:[1,0] neg_lo:[0,1] neg_hi:[0,1]
	v_max_f32_e32 v204, v203, v203
	v_max_f32_e32 v204, 0, v204
	v_cndmask_b32_e64 v204, v204, v203, s[64:65]
	v_exp_f32_e64 v208, -v204
	v_mov_b32_e32 v209, v206
	v_pk_mul_f32 v[62:63], v[62:63], v[206:207] op_sel_hi:[1,0]
	v_pk_mul_f32 v[60:61], v[60:61], v[206:207] op_sel_hi:[1,0]
	v_pk_mul_f32 v[58:59], v[58:59], v[206:207] op_sel_hi:[1,0]
	v_pk_mul_f32 v[56:57], v[56:57], v[206:207] op_sel_hi:[1,0]
	v_pk_mul_f32 v[54:55], v[54:55], v[206:207] op_sel_hi:[1,0]
	v_pk_mul_f32 v[52:53], v[52:53], v[206:207] op_sel_hi:[1,0]
	v_pk_mul_f32 v[50:51], v[50:51], v[206:207] op_sel_hi:[1,0]
	v_pk_mul_f32 v[48:49], v[48:49], v[206:207] op_sel_hi:[1,0]
	v_pk_mul_f32 v[46:47], v[46:47], v[206:207] op_sel_hi:[1,0]
	v_pk_mul_f32 v[44:45], v[44:45], v[206:207] op_sel_hi:[1,0]
	v_pk_mul_f32 v[42:43], v[42:43], v[206:207] op_sel_hi:[1,0]
	v_pk_mul_f32 v[40:41], v[40:41], v[206:207] op_sel_hi:[1,0]
	v_pk_mul_f32 v[38:39], v[38:39], v[206:207] op_sel_hi:[1,0]
	v_pk_mul_f32 v[36:37], v[36:37], v[206:207] op_sel_hi:[1,0]
	v_pk_mul_f32 v[34:35], v[34:35], v[206:207] op_sel_hi:[1,0]
	v_pk_mul_f32 v[32:33], v[32:33], v[206:207] op_sel_hi:[1,0]
	v_add_f32_e32 v200, v200, v204
	v_pk_mul_f32 v[150:151], v[150:151], v[208:209]
	v_pk_add_f32 v[64:65], v[64:65], v[204:205] op_sel_hi:[1,0] neg_lo:[0,1] neg_hi:[0,1]
	v_pk_add_f32 v[66:67], v[66:67], v[204:205] op_sel_hi:[1,0] neg_lo:[0,1] neg_hi:[0,1]
	v_pk_add_f32 v[68:69], v[68:69], v[204:205] op_sel_hi:[1,0] neg_lo:[0,1] neg_hi:[0,1]
	v_pk_add_f32 v[70:71], v[70:71], v[204:205] op_sel_hi:[1,0] neg_lo:[0,1] neg_hi:[0,1]
	v_pk_add_f32 v[72:73], v[72:73], v[204:205] op_sel_hi:[1,0] neg_lo:[0,1] neg_hi:[0,1]
	v_pk_add_f32 v[74:75], v[74:75], v[204:205] op_sel_hi:[1,0] neg_lo:[0,1] neg_hi:[0,1]
	v_pk_add_f32 v[76:77], v[76:77], v[204:205] op_sel_hi:[1,0] neg_lo:[0,1] neg_hi:[0,1]
	v_pk_add_f32 v[78:79], v[78:79], v[204:205] op_sel_hi:[1,0] neg_lo:[0,1] neg_hi:[0,1]
	v_pk_mul_f32 v[30:31], v[30:31], v[208:209] op_sel_hi:[1,0]
	v_pk_mul_f32 v[28:29], v[28:29], v[208:209] op_sel_hi:[1,0]
	v_pk_mul_f32 v[26:27], v[26:27], v[208:209] op_sel_hi:[1,0]
	v_pk_mul_f32 v[24:25], v[24:25], v[208:209] op_sel_hi:[1,0]
	v_pk_mul_f32 v[22:23], v[22:23], v[208:209] op_sel_hi:[1,0]
	v_pk_mul_f32 v[20:21], v[20:21], v[208:209] op_sel_hi:[1,0]
	v_pk_mul_f32 v[18:19], v[18:19], v[208:209] op_sel_hi:[1,0]
	v_pk_mul_f32 v[16:17], v[16:17], v[208:209] op_sel_hi:[1,0]
	v_pk_mul_f32 v[14:15], v[14:15], v[208:209] op_sel_hi:[1,0]
	v_pk_mul_f32 v[12:13], v[12:13], v[208:209] op_sel_hi:[1,0]
	v_pk_mul_f32 v[10:11], v[10:11], v[208:209] op_sel_hi:[1,0]
	v_pk_mul_f32 v[8:9], v[8:9], v[208:209] op_sel_hi:[1,0]
	v_pk_mul_f32 v[6:7], v[6:7], v[208:209] op_sel_hi:[1,0]
	v_pk_mul_f32 v[4:5], v[4:5], v[208:209] op_sel_hi:[1,0]
	v_pk_mul_f32 v[2:3], v[2:3], v[208:209] op_sel_hi:[1,0]
	v_pk_mul_f32 v[0:1], v[0:1], v[208:209] op_sel_hi:[1,0]
	s_mov_b64 s[62:63], -1

.LBB0_2119:
	s_nop 10
	v_max_f32_e32 v203, v80, v81
	v_max_f32_e32 v205, v64, v65
	v_max3_f32 v203, v203, v82, v83
	v_max3_f32 v205, v205, v66, v67
	v_max3_f32 v203, v203, v84, v85
	v_max3_f32 v205, v205, v68, v69
	v_max3_f32 v203, v203, v86, v87
	v_max3_f32 v205, v205, v70, v71
	v_max3_f32 v203, v203, v88, v89
	v_max3_f32 v205, v205, v72, v73
	v_max3_f32 v203, v203, v90, v91
	v_max3_f32 v205, v205, v74, v75
	v_max3_f32 v203, v203, v92, v93
	v_max3_f32 v205, v205, v76, v77
	v_max3_f32 v203, v203, v94, v95
	v_max3_f32 v205, v205, v78, v79
	s_nop 1
	v_permlane32_swap_b32_e32 v203, v205
	v_max_f32_e32 v204, v203, v205
	v_cmp_lt_f32_e32 vcc, s82, v204
	s_cmp_lg_u64 s[64:65], 0
	s_cbranch_scc1 .Lhwat1_firstchk
	s_cbranch_vccz .LBB0_2121
	s_branch .Lhwat1_rare
.Lhwat1_firstchk:
	v_cmp_gt_f32_e64 s[34:35], s83, v204
	s_or_b64 s[30:31], vcc, s[34:35]
	s_and_b64 vcc, exec, s[30:31]
	s_cbranch_vccz .LBB0_2121
